# sample-attention loop: one static priority raise for waves 4-7 (the second wave on each SIMD), reset at loop exit
# speedup vs baseline: 1.0047x; 1.0031x over previous
; __device__ __forceinline__ void sattn_unit(const Args& a, LAS unsigned char* lds, const LAS float* bt, int db, int h, int t, int tid, int wave, int lane) {
;     ...
;     const int tile0 = ksp * 33, nf = ksp ? 31 : 33;
;     SA_LOAD(tile0 * 32);
;     for (int it = 0; it < nf; ++it) {
.Lks_m0:
	v_readlane_b32 s34, v251, 10
	s_cmp_lt_u32 s34, 4
	s_cbranch_scc1 .Lsp_skip
	s_setprio 1
.Lsp_skip:
	v_mbcnt_lo_u32_b32 v250, -1, 0
	v_mbcnt_hi_u32_b32 v250, -1, v250
	s_lshr_b32 s14, s34, 2
	s_lshl_b32 s14, s14, 14
	s_add_i32 s14, s14, 0x12800
	s_bfe_u32 s15, s34, 0x10001
	s_lshl_b32 s15, s15, 12
	s_add_i32 s15, s15, s14
	v_lshrrev_b32_e32 v74, 5, v250
	v_and_b32_e32 v75, 31, v250
	v_lshlrev_b32_e32 v73, 8, v74
	v_lshl_add_u32 v73, v75, 1, v73
	v_add_u32_e32 v73, s15, v73
	v_cvt_pk_bf16_f32 v72, v176, v176
	ds_write_b16 v73, v72 offset:0
	v_cvt_pk_bf16_f32 v72, v179, v179
	ds_write_b16 v73, v72 offset:64
	v_cvt_pk_bf16_f32 v72, v195, v195
	ds_write_b16 v73, v72 offset:128
	v_cvt_pk_bf16_f32 v72, v204, v204
	ds_write_b16 v73, v72 offset:192
	v_cvt_pk_bf16_f32 v72, v219, v219
	ds_write_b16 v73, v72 offset:512
	v_cvt_pk_bf16_f32 v72, v228, v228
	ds_write_b16 v73, v72 offset:576
	v_cvt_pk_bf16_f32 v72, v239, v239
	ds_write_b16 v73, v72 offset:640
	v_cvt_pk_bf16_f32 v72, v242, v242
	ds_write_b16 v73, v72 offset:704
	v_cvt_pk_bf16_f32 v72, v175, v175
	ds_write_b16 v73, v72 offset:1024
	v_cvt_pk_bf16_f32 v72, v178, v178
	ds_write_b16 v73, v72 offset:1088
	v_cvt_pk_bf16_f32 v72, v186, v186
	ds_write_b16 v73, v72 offset:1152
	v_cvt_pk_bf16_f32 v72, v202, v202
	ds_write_b16 v73, v72 offset:1216
	v_cvt_pk_bf16_f32 v72, v218, v218
	ds_write_b16 v73, v72 offset:1536
	v_cvt_pk_bf16_f32 v72, v226, v226
	ds_write_b16 v73, v72 offset:1600
	v_cvt_pk_bf16_f32 v72, v238, v238
	ds_write_b16 v73, v72 offset:1664
	v_cvt_pk_bf16_f32 v72, v241, v241
	ds_write_b16 v73, v72 offset:1728
	v_cvt_pk_bf16_f32 v72, v174, v174
	ds_write_b16 v73, v72 offset:2048
	v_cvt_pk_bf16_f32 v72, v177, v177
	ds_write_b16 v73, v72 offset:2112
	v_cvt_pk_bf16_f32 v72, v184, v184
	ds_write_b16 v73, v72 offset:2176
	v_cvt_pk_bf16_f32 v72, v200, v200
	ds_write_b16 v73, v72 offset:2240
	v_cvt_pk_bf16_f32 v72, v216, v216
	ds_write_b16 v73, v72 offset:2560
	v_cvt_pk_bf16_f32 v72, v224, v224
	ds_write_b16 v73, v72 offset:2624
	v_cvt_pk_bf16_f32 v72, v237, v237
	ds_write_b16 v73, v72 offset:2688
	v_cvt_pk_bf16_f32 v72, v240, v240
	ds_write_b16 v73, v72 offset:2752
	v_cvt_pk_bf16_f32 v72, v173, v173
	ds_write_b16 v73, v72 offset:3072
	v_cvt_pk_bf16_f32 v72, v180, v180
	ds_write_b16 v73, v72 offset:3136
	v_cvt_pk_bf16_f32 v72, v183, v183
	ds_write_b16 v73, v72 offset:3200
	v_cvt_pk_bf16_f32 v72, v207, v207
	ds_write_b16 v73, v72 offset:3264
	v_cvt_pk_bf16_f32 v72, v214, v214
	ds_write_b16 v73, v72 offset:3584
	v_cvt_pk_bf16_f32 v72, v231, v231
	ds_write_b16 v73, v72 offset:3648
	v_cvt_pk_bf16_f32 v72, v236, v236
	ds_write_b16 v73, v72 offset:3712
	v_cvt_pk_bf16_f32 v72, v243, v243
	ds_write_b16 v73, v72 offset:3776
	v_bfe_u32 v76, v250, 4, 1
	v_lshlrev_b32_e32 v76, 5, v76
	v_and_b32_e32 v77, 3, v250
	v_lshl_add_u32 v76, v77, 3, v76
	v_bfe_u32 v77, v250, 2, 2
	v_lshl_add_u32 v77, v74, 2, v77
	v_lshl_add_u32 v249, v77, 6, v76
	v_add_u32_e32 v249, s15, v249
	s_and_b32 s15, s34, 3
	s_lshl_b32 s48, s15, 9
	s_add_i32 s48, s48, s14
	v_lshrrev_b32_e32 v76, 3, v75
	v_lshlrev_b32_e32 v76, 11, v76
	v_lshl_add_u32 v76, v74, 6, v76
	v_and_b32_e32 v77, 7, v250
	v_lshl_add_u32 v248, v77, 3, v76
	v_add_u32_e32 v248, s48, v248
	s_lshl_b32 s15, s15, 15
	v_lshlrev_b32_e32 v76, 12, v74
	v_lshl_add_u32 v250, v75, 4, v76
	v_add_u32_e32 v250, s15, v250
	s_mov_b32 s34, 0x2000
	s_lshl_b32 s81, s81, 15
	s_movk_i32 s32, 0x2200

; __device__ __forceinline__ int crow(int r,int hi){return (r&3)+8*(r>>2)+4*hi;}
; __device__ __forceinline__ int crow(int r, int hi) { return (r & 3) + 8 * (r >> 2) + 4 * hi; }
; __device__ __forceinline__ void sattn_unit(const Args& a, LAS unsigned char* lds, const LAS float* bt, int db, int h, int t, int tid, int wave, int lane) {
;     ...
;     if (ksp == 1) {
;         for (int it = 0; it < 2; ++it) {
;             const int key0 = 2048 + it * 32;
;             bf16x8 kf[4]; bf16x8 vf[2][2];
;             const bf16* kpu = Kb + (size_t)(MP + db * 64 + key0 - 2048) * 1024 + h * 128 + t * 64;
;             const bf16* vpu = Vb + (size_t)(MP + db * 64 + key0 - 2048) * 1024 + h * 128;
; #pragma unroll
;             for (int d0 = 0; d0 < 4; ++d0) kf[d0] = *(const bf16x8*)(kpu + (klo + d0 * 16));
; #pragma unroll
;             for (int e = 0; e < 8; ++e) { const bf16* r0 = vpu + crow(e, 0) * 1024; const bf16* r1 = vpu + (16 + crow(e, 0)) * 1024;
; #pragma unroll
;                 for (int d2 = 0; d2 < 2; ++d2) { vf[d2][0][e] = (short)r0[vlo + d2 * 32]; vf[d2][1][e] = (short)r1[vlo + d2 * 32]; } }
;             SA_COMPUTE(key0);
.LBB0_303:
	s_setprio 0
	v_cndmask_b32_e64 v32, 0, 1, s[26:27]
	v_cmp_ne_u32_e64 s[0:1], 1, v32
	s_andn2_b64 vcc, exec, s[26:27]
	s_cbranch_vccnz .LBB0_309
	s_barrier
	s_barrier
	s_lshl_b32 s5, s5, 1
	v_readlane_b32 s14, v251, 26
	s_add_u32 s14, s14, s5
	v_readlane_b32 s15, v251, 28
	s_addc_u32 s15, s15, 0
	s_lshl_b32 s7, s7, 1
	s_add_u32 s89, s14, s7
	s_addc_u32 s93, s15, 0
	s_add_u32 s30, s82, s5
	v_readlane_b32 s5, v251, 32
	s_addc_u32 s35, s5, 0
	s_ashr_i32 s7, s6, 31
	s_lshl_b64 s[6:7], s[6:7], 11
	s_add_u32 vcc_lo, s89, s6
	v_lshl_add_u32 v112, v159, 10, v114
	s_addc_u32 vcc_hi, s93, s7
	v_lshl_add_u64 v[32:33], v[112:113], 1, vcc
	global_load_dwordx4 v[32:35], v[32:33], off
	s_waitcnt vmcnt(35)
	v_add_u32_e32 v84, 16, v112
	v_mov_b32_e32 v85, v113
	v_lshl_add_u64 v[36:37], v[84:85], 1, vcc
	global_load_dwordx4 v[72:75], v[36:37], off
	v_add_u32_e32 v80, 32, v112
	v_mov_b32_e32 v81, v113
	v_lshl_add_u64 v[36:37], v[80:81], 1, vcc
	global_load_dwordx4 v[68:71], v[36:37], off
	v_add_u32_e32 v82, 48, v112
	v_mov_b32_e32 v83, v113
	v_lshl_add_u64 v[36:37], v[82:83], 1, vcc
	global_load_dwordx4 v[64:67], v[36:37], off
	s_add_u32 s6, s30, s6
	s_addc_u32 s7, s35, s7
	s_add_u32 vcc_lo, s6, 0x8000
	s_addc_u32 vcc_hi, s7, 0
	v_lshlrev_b64 v[76:77], 1, v[116:117]
	v_lshl_add_u64 v[36:37], s[6:7], 0, v[76:77]
	v_lshl_add_u64 v[38:39], vcc, 0, v[76:77]
	v_lshlrev_b64 v[78:79], 1, v[118:119]
	global_load_ushort v91, v[36:37], off
	global_load_ushort v89, v[38:39], off
	global_load_ushort v87, v[36:37], off offset:64
	v_lshl_add_u64 v[38:39], vcc, 0, v[78:79]
	s_add_u32 vcc_lo, s6, 0x8800
	s_addc_u32 vcc_hi, s7, 0
	global_load_ushort v88, v[38:39], off
	global_load_ushort v94, v[36:37], off offset:2048
	v_lshl_add_u64 v[38:39], vcc, 0, v[76:77]
	global_load_ushort v92, v[38:39], off
	global_load_ushort v90, v[36:37], off offset:2112
	v_lshl_add_u64 v[36:37], vcc, 0, v[78:79]
	s_add_u32 vcc_lo, s6, 0x1000
	s_addc_u32 vcc_hi, s7, 0
	s_add_u32 s48, s6, 0x9000
	global_load_ushort v93, v[36:37], off
	s_addc_u32 s49, s7, 0
	v_lshl_add_u64 v[36:37], vcc, 0, v[76:77]
	global_load_ushort v98, v[36:37], off
	v_lshl_add_u64 v[36:37], s[48:49], 0, v[76:77]
	global_load_ushort v97, v[36:37], off
	v_lshl_add_u64 v[36:37], vcc, 0, v[78:79]
	global_load_ushort v95, v[36:37], off
	v_lshl_add_u64 v[36:37], s[48:49], 0, v[78:79]
	s_add_u32 s48, s6, 0x1800
	s_addc_u32 s49, s7, 0
	s_add_u32 vcc_lo, s6, 0x9800
	global_load_ushort v96, v[36:37], off
	s_addc_u32 vcc_hi, s7, 0
	v_lshl_add_u64 v[36:37], s[48:49], 0, v[76:77]
	global_load_ushort v102, v[36:37], off
	v_lshl_add_u64 v[36:37], vcc, 0, v[76:77]
	global_load_ushort v100, v[36:37], off
	v_lshl_add_u64 v[36:37], s[48:49], 0, v[78:79]
	s_add_u32 s48, s6, 0x4000
	s_addc_u32 s49, s7, 0
	global_load_ushort v99, v[36:37], off
	v_lshl_add_u64 v[36:37], vcc, 0, v[78:79]
	s_add_u32 vcc_lo, s6, 0xc000
	global_load_ushort v101, v[36:37], off
	s_addc_u32 vcc_hi, s7, 0
	v_lshl_add_u64 v[36:37], s[48:49], 0, v[76:77]
	global_load_ushort v107, v[36:37], off
	v_lshl_add_u64 v[36:37], vcc, 0, v[76:77]
	global_load_ushort v106, v[36:37], off
	v_lshl_add_u64 v[36:37], s[48:49], 0, v[78:79]
	s_add_u32 s48, s6, 0x4800
	s_addc_u32 s49, s7, 0
	global_load_ushort v103, v[36:37], off
	v_lshl_add_u64 v[36:37], vcc, 0, v[78:79]
	s_add_u32 vcc_lo, s6, 0xc800
	global_load_ushort v105, v[36:37], off
	s_addc_u32 vcc_hi, s7, 0
	v_lshl_add_u64 v[36:37], s[48:49], 0, v[76:77]
	global_load_ushort v111, v[36:37], off
	v_lshl_add_u64 v[36:37], vcc, 0, v[76:77]
	global_load_ushort v109, v[36:37], off
	v_lshl_add_u64 v[36:37], s[48:49], 0, v[78:79]
	s_add_u32 s48, s6, 0x5000
	s_addc_u32 s49, s7, 0
	v_lshl_add_u64 v[118:119], s[48:49], 0, v[78:79]
	global_load_ushort v108, v[36:37], off
	s_nop 0
	global_load_ushort v118, v[118:119], off
	v_lshl_add_u64 v[36:37], vcc, 0, v[78:79]
	s_add_u32 vcc_lo, s6, 0xd000
	s_addc_u32 vcc_hi, s7, 0
	v_lshl_add_u64 v[120:121], vcc, 0, v[78:79]
	global_load_ushort v110, v[36:37], off
	global_load_ushort v117, v[120:121], off
	v_lshl_add_u64 v[36:37], s[48:49], 0, v[76:77]
	global_load_ushort v116, v[36:37], off
	v_lshl_add_u64 v[36:37], vcc, 0, v[76:77]
	global_load_ushort v114, v[36:37], off
	s_waitcnt vmcnt(31)
	v_mfma_f32_32x32x16_bf16 v[32:47], v[32:35], v[60:63], 0
	s_add_u32 s48, s6, 0x5800
	s_addc_u32 s49, s7, 0
	s_add_u32 s6, s6, 0xd800
	s_addc_u32 s7, s7, 0
	v_lshl_add_u64 v[120:121], s[48:49], 0, v[78:79]
	s_waitcnt vmcnt(30)
	v_mfma_f32_32x32x16_bf16 v[32:47], v[72:75], v[56:59], v[32:47]
	v_lshl_add_u64 v[72:73], s[48:49], 0, v[76:77]
	global_load_ushort v74, v[72:73], off
	s_waitcnt vmcnt(30)
	v_mfma_f32_32x32x16_bf16 v[32:47], v[68:71], v[52:55], v[32:47]
	v_lshl_add_u64 v[68:69], s[6:7], 0, v[78:79]
	global_load_ushort v68, v[68:69], off
	v_lshl_add_u64 v[72:73], s[6:7], 0, v[76:77]
	global_load_ushort v73, v[72:73], off
	v_max_i32_e32 v69, 0xffffff80, v168
	global_load_ushort v72, v[120:121], off
	v_add_u32_e32 v69, 0x80, v69
	s_waitcnt vmcnt(32)
	v_mfma_f32_32x32x16_bf16 v[32:47], v[64:67], v[48:51], v[32:47]
	v_max_i32_e32 v64, 0xffffff7f, v168
	v_max_i32_e32 v65, 0xffffff7e, v168
	v_add_u32_e32 v64, 0x81, v64
	v_add_u32_e32 v65, 0x82, v65
	v_min_u32_e32 v69, 0xc0, v69
	v_min_u32_e32 v64, 0xc0, v64
	v_min_u32_e32 v65, 0xc0, v65
	v_lshl_add_u32 v69, v69, 2, s92
	v_lshl_add_u32 v64, v64, 2, s92
	v_lshl_add_u32 v65, v65, 2, s92
	ds_read_b32 v69, v69
	ds_read_b32 v64, v64
	ds_read_b32 v66, v65
	v_max_i32_e32 v65, 0xffffff7d, v168
	v_add_u32_e32 v65, 0x83, v65
	v_min_u32_e32 v65, 0xc0, v65
	v_lshl_add_u32 v65, v65, 2, s92
	ds_read_b32 v67, v65
	v_max_i32_e32 v65, 0xffffff78, v168
	v_add_u32_e32 v65, 0x88, v65
	v_min_u32_e32 v65, 0xc0, v65
	v_lshl_add_u32 v65, v65, 2, s92
	s_waitcnt lgkmcnt(3)
	v_add_f32_e32 v32, v32, v69
	ds_read_b32 v69, v65
	v_max_i32_e32 v65, 0xffffff77, v168
	v_add_u32_e32 v65, 0x89, v65
	v_min_u32_e32 v65, 0xc0, v65
	v_lshl_add_u32 v65, v65, 2, s92
	ds_read_b32 v70, v65
	s_waitcnt lgkmcnt(4)
	v_add_f32_e32 v65, v33, v64
	s_waitcnt lgkmcnt(3)
	v_add_f32_e32 v64, v34, v66
	s_waitcnt lgkmcnt(1)
	v_add_f32_e32 v34, v36, v69
	v_max_i32_e32 v36, 0xffffff76, v168
	s_waitcnt lgkmcnt(0)
	v_add_f32_e32 v33, v37, v70
	v_max_i32_e32 v37, 0xffffff75, v168
	v_max_i32_e32 v66, 0xffffff70, v168
	v_add_u32_e32 v36, 0x8a, v36
	v_add_u32_e32 v37, 0x8b, v37
	v_add_u32_e32 v66, 0x90, v66
	v_min_u32_e32 v36, 0xc0, v36
	v_min_u32_e32 v37, 0xc0, v37
	v_min_u32_e32 v66, 0xc0, v66
	v_lshl_add_u32 v36, v36, 2, s92
	v_lshl_add_u32 v37, v37, 2, s92
	v_lshl_add_u32 v66, v66, 2, s92
	v_add_f32_e32 v35, v35, v67
	ds_read_b32 v36, v36
	ds_read_b32 v37, v37
	ds_read_b32 v67, v66
	v_max_i32_e32 v66, 0xffffff6f, v168
	v_add_u32_e32 v66, 0x91, v66
	v_min_u32_e32 v66, 0xc0, v66
	v_lshl_add_u32 v66, v66, 2, s92
	ds_read_b32 v69, v66
	v_max_i32_e32 v66, 0xffffff6e, v168
	v_add_u32_e32 v66, 0x92, v66
	v_min_u32_e32 v66, 0xc0, v66
	v_lshl_add_u32 v66, v66, 2, s92
	ds_read_b32 v70, v66
	s_waitcnt lgkmcnt(4)
	v_add_f32_e32 v66, v38, v36
	s_waitcnt lgkmcnt(3)
	v_add_f32_e32 v39, v39, v37
	s_waitcnt lgkmcnt(2)
	v_add_f32_e32 v38, v40, v67
	s_waitcnt lgkmcnt(1)
	v_add_f32_e32 v37, v41, v69
	v_max_i32_e32 v40, 0xffffff6d, v168
	v_max_i32_e32 v41, 0xffffff68, v168
	s_waitcnt lgkmcnt(0)
	v_add_f32_e32 v36, v42, v70
	v_add_u32_e32 v40, 0x93, v40
	v_add_u32_e32 v41, 0x98, v41
	v_max_i32_e32 v42, 0xffffff67, v168
	v_max_i32_e32 v67, 0xffffff66, v168
	v_min_u32_e32 v40, 0xc0, v40
	v_min_u32_e32 v41, 0xc0, v41
	v_add_u32_e32 v42, 0x99, v42
	v_add_u32_e32 v67, 0x9a, v67
	v_lshl_add_u32 v40, v40, 2, s92
	v_lshl_add_u32 v41, v41, 2, s92
	v_min_u32_e32 v42, 0xc0, v42
	v_min_u32_e32 v67, 0xc0, v67
	ds_read_b32 v40, v40
	ds_read_b32 v41, v41
	v_lshl_add_u32 v42, v42, 2, s92
	v_lshl_add_u32 v67, v67, 2, s92
	ds_read_b32 v42, v42
	ds_read_b32 v69, v67
	v_max_i32_e32 v67, 0xffffff65, v168
	v_add_u32_e32 v67, 0x9b, v67
	v_min_u32_e32 v67, 0xc0, v67
	v_lshl_add_u32 v67, v67, 2, s92
	ds_read_b32 v70, v67
	s_waitcnt lgkmcnt(4)
	v_add_f32_e32 v67, v43, v40
	s_waitcnt lgkmcnt(3)
	v_add_f32_e32 v43, v44, v41
	v_max3_f32 v44, v32, s31, v65
	v_max3_f32 v44, v44, v64, v35
	v_max3_f32 v44, v44, v34, v33
	v_max3_f32 v44, v44, v66, v39
	v_max3_f32 v44, v44, v38, v37
	s_waitcnt lgkmcnt(2)
	v_add_f32_e32 v42, v45, v42
	v_max3_f32 v44, v44, v36, v67
	s_waitcnt lgkmcnt(1)
	v_add_f32_e32 v40, v46, v69
	s_waitcnt lgkmcnt(0)
	v_add_f32_e32 v41, v47, v70
	v_max3_f32 v44, v44, v43, v42
	v_max3_f32 v44, v44, v40, v41
	ds_bpermute_b32 v45, v194, v44
	s_waitcnt lgkmcnt(0)
	v_max3_f32 v86, v104, v44, v45
	v_cmp_gt_f32_e32 vcc, v86, v104
	s_cbranch_vccz .LBB0_306
	v_sub_f32_e32 v44, v104, v86
	v_exp_f32_e32 v69, v44
	ds_bpermute_b32 v44, v164, v69
	ds_bpermute_b32 v45, v165, v69
	ds_bpermute_b32 v46, v166, v69
	ds_bpermute_b32 v47, v167, v69
	ds_bpermute_b32 v70, v162, v69
	ds_bpermute_b32 v71, v158, v69
	ds_bpermute_b32 v120, v156, v69
	ds_bpermute_b32 v122, v152, v69
	ds_bpermute_b32 v124, v148, v69
	ds_bpermute_b32 v126, v144, v69
	ds_bpermute_b32 v128, v140, v69
	ds_bpermute_b32 v129, v138, v69
	ds_bpermute_b32 v127, v142, v69
	ds_bpermute_b32 v125, v146, v69
	ds_bpermute_b32 v123, v150, v69
	ds_bpermute_b32 v121, v154, v69
	s_waitcnt lgkmcnt(4)
	v_pk_mul_f32 v[14:15], v[14:15], v[128:129]
	s_waitcnt lgkmcnt(3)
	v_pk_mul_f32 v[12:13], v[12:13], v[126:127]
	s_waitcnt lgkmcnt(2)
	v_pk_mul_f32 v[10:11], v[10:11], v[124:125]
	s_waitcnt lgkmcnt(1)
	v_pk_mul_f32 v[8:9], v[8:9], v[122:123]
	s_waitcnt lgkmcnt(0)
	v_pk_mul_f32 v[6:7], v[6:7], v[120:121]
	v_pk_mul_f32 v[4:5], v[4:5], v[70:71]
	v_pk_mul_f32 v[2:3], v[2:3], v[46:47]
	v_pk_mul_f32 v[0:1], v[0:1], v[44:45]
	v_pk_mul_f32 v[30:31], v[30:31], v[128:129]
	v_pk_mul_f32 v[28:29], v[28:29], v[126:127]
	v_pk_mul_f32 v[26:27], v[26:27], v[124:125]
	v_pk_mul_f32 v[24:25], v[24:25], v[122:123]
	v_pk_mul_f32 v[22:23], v[22:23], v[120:121]
	v_pk_mul_f32 v[20:21], v[20:21], v[70:71]
	v_pk_mul_f32 v[18:19], v[18:19], v[46:47]
	v_pk_mul_f32 v[16:17], v[16:17], v[44:45]
	v_mul_f32_e32 v169, v169, v69
